# v40 + K-fragment ds_reads hoisted above the row-max chain
# speedup vs baseline: 1.0038x; 1.0038x over previous
.LBB0_1181:
	ds_read_b128 v[10:13], v154 offset:16384
	ds_read_b128 v[4:7], v154 offset:24576
	ds_read_b128 v[170:173], v155 offset:16384
	ds_read_b128 v[174:177], v155 offset:24576
	ds_read_b128 v[182:185], v156 offset:16384
	ds_read_b128 v[186:189], v156 offset:24576
	ds_read_b128 v[194:197], v157 offset:16384
	ds_read_b128 v[226:229], v157 offset:24576
	v_max3_f32 v0, v96, v80, v97
	v_max3_f32 v1, v81, v98, v82
	s_cmp_eq_u32 s73, 0
	v_max3_f32 v0, v0, v99, v83
	v_max3_f32 v1, v1, v100, v84
	s_mov_b32 s3, 0xc2400000
	v_max3_f32 v0, v0, v101, v85
	v_max3_f32 v1, v1, v102, v86
	s_cselect_b64 s[42:43], -1, 0
	v_max3_f32 v0, v0, v103, v87
	v_max3_f32 v1, v1, v104, v88
	s_nop 0
	v_max3_f32 v0, v0, v105, v89
	v_max3_f32 v1, v1, v106, v90
	s_nop 0
	v_max3_f32 v0, v0, v107, v91
	v_max3_f32 v1, v1, v108, v92
	s_nop 0
	v_max3_f32 v0, v0, v109, v93
	v_max3_f32 v1, v1, v110, v94
	s_nop 0
	v_max3_f32 v0, v0, v1, v111
	v_max_f32_e32 v0, v0, v95
	v_mov_b32_e32 v1, v0
	s_nop 1
	v_permlane32_swap_b32_e32 v0, v1
	v_max_f32_e32 v0, v0, v1
	v_cmp_gt_f32_e64 s[44:45], s3, v0
	v_cmp_lt_f32_e32 vcc, s37, v0
	s_and_b64 s[44:45], s[42:43], s[44:45]
	s_or_b64 vcc, vcc, s[44:45]
	s_cbranch_vccz .LBB0_1183
	v_max_f32_e32 v1, v0, v0
	v_max_f32_e32 v1, 0, v1
	v_cndmask_b32_e64 v1, v1, v0, s[42:43]
	v_exp_f32_e64 v0, -v1
	v_add_f32_e32 v165, v165, v1
	v_sub_f32_e32 v111, v111, v1
	v_sub_f32_e32 v110, v110, v1
	v_cndmask_b32_e64 v0, v0, 1.0, s[42:43]
	v_pk_mul_f32 v[62:63], v[62:63], v[0:1] op_sel_hi:[1,0]
	v_pk_mul_f32 v[60:61], v[60:61], v[0:1] op_sel_hi:[1,0]
	v_pk_mul_f32 v[58:59], v[58:59], v[0:1] op_sel_hi:[1,0]
	v_pk_mul_f32 v[56:57], v[56:57], v[0:1] op_sel_hi:[1,0]
	v_pk_mul_f32 v[54:55], v[54:55], v[0:1] op_sel_hi:[1,0]
	v_pk_mul_f32 v[52:53], v[52:53], v[0:1] op_sel_hi:[1,0]
	v_pk_mul_f32 v[50:51], v[50:51], v[0:1] op_sel_hi:[1,0]
	v_pk_mul_f32 v[48:49], v[48:49], v[0:1] op_sel_hi:[1,0]
	v_pk_mul_f32 v[78:79], v[78:79], v[0:1] op_sel_hi:[1,0]
	v_pk_mul_f32 v[76:77], v[76:77], v[0:1] op_sel_hi:[1,0]
	v_pk_mul_f32 v[74:75], v[74:75], v[0:1] op_sel_hi:[1,0]
	v_pk_mul_f32 v[72:73], v[72:73], v[0:1] op_sel_hi:[1,0]
	v_pk_mul_f32 v[70:71], v[70:71], v[0:1] op_sel_hi:[1,0]
	v_pk_mul_f32 v[68:69], v[68:69], v[0:1] op_sel_hi:[1,0]
	v_pk_mul_f32 v[66:67], v[66:67], v[0:1] op_sel_hi:[1,0]
	v_pk_mul_f32 v[64:65], v[64:65], v[0:1] op_sel_hi:[1,0]
	v_pk_mul_f32 v[46:47], v[46:47], v[0:1] op_sel_hi:[1,0]
	v_pk_mul_f32 v[44:45], v[44:45], v[0:1] op_sel_hi:[1,0]
	v_pk_mul_f32 v[42:43], v[42:43], v[0:1] op_sel_hi:[1,0]
	v_pk_mul_f32 v[40:41], v[40:41], v[0:1] op_sel_hi:[1,0]
	v_pk_mul_f32 v[38:39], v[38:39], v[0:1] op_sel_hi:[1,0]
	v_pk_mul_f32 v[36:37], v[36:37], v[0:1] op_sel_hi:[1,0]
	v_pk_mul_f32 v[34:35], v[34:35], v[0:1] op_sel_hi:[1,0]
	v_pk_mul_f32 v[32:33], v[32:33], v[0:1] op_sel_hi:[1,0]
	v_pk_mul_f32 v[30:31], v[30:31], v[0:1] op_sel_hi:[1,0]
	v_pk_mul_f32 v[28:29], v[28:29], v[0:1] op_sel_hi:[1,0]
	v_pk_mul_f32 v[26:27], v[26:27], v[0:1] op_sel_hi:[1,0]
	v_pk_mul_f32 v[24:25], v[24:25], v[0:1] op_sel_hi:[1,0]
	v_pk_mul_f32 v[22:23], v[22:23], v[0:1] op_sel_hi:[1,0]
	v_pk_mul_f32 v[20:21], v[20:21], v[0:1] op_sel_hi:[1,0]
	v_pk_mul_f32 v[18:19], v[18:19], v[0:1] op_sel_hi:[1,0]
	v_pk_mul_f32 v[16:17], v[16:17], v[0:1] op_sel_hi:[1,0]
	v_sub_f32_e32 v109, v109, v1
	v_sub_f32_e32 v108, v108, v1
	v_sub_f32_e32 v107, v107, v1
	v_sub_f32_e32 v106, v106, v1
	v_sub_f32_e32 v105, v105, v1
	v_sub_f32_e32 v104, v104, v1
	v_sub_f32_e32 v103, v103, v1
	v_sub_f32_e32 v102, v102, v1
	v_sub_f32_e32 v101, v101, v1
	v_sub_f32_e32 v100, v100, v1
	v_sub_f32_e32 v99, v99, v1
	v_sub_f32_e32 v98, v98, v1
	v_sub_f32_e32 v97, v97, v1
	v_sub_f32_e32 v96, v96, v1
	v_sub_f32_e32 v95, v95, v1
	v_sub_f32_e32 v94, v94, v1
	v_sub_f32_e32 v93, v93, v1
	v_sub_f32_e32 v92, v92, v1
	v_sub_f32_e32 v91, v91, v1
	v_sub_f32_e32 v90, v90, v1
	v_sub_f32_e32 v89, v89, v1
	v_sub_f32_e32 v88, v88, v1
	v_sub_f32_e32 v87, v87, v1
	v_sub_f32_e32 v86, v86, v1
	v_sub_f32_e32 v85, v85, v1
	v_sub_f32_e32 v84, v84, v1
	v_sub_f32_e32 v83, v83, v1
	v_sub_f32_e32 v82, v82, v1
	v_sub_f32_e32 v81, v81, v1
	v_sub_f32_e32 v80, v80, v1
	v_mul_f32_e32 v161, v161, v0
.LBB0_1183:
	s_andn2_b64 s[42:43], exec, s[70:71]
	s_andn2_b64 vcc, exec, s[70:71]
	s_cbranch_vccnz .LBB0_1185
	s_waitcnt lgkmcnt(6)
	v_mfma_f32_32x32x16_bf16 v[128:143], v[10:13], v[238:241], 0
	v_mfma_f32_32x32x16_bf16 v[112:127], v[4:7], v[238:241], 0
	s_waitcnt lgkmcnt(4)
	v_mfma_f32_32x32x16_bf16 v[128:143], v[170:173], v[242:245], v[128:143]
	v_mfma_f32_32x32x16_bf16 v[112:127], v[174:177], v[242:245], v[112:127]
	s_waitcnt lgkmcnt(2)
	v_mfma_f32_32x32x16_bf16 v[128:143], v[182:185], v[246:249], v[128:143]
	v_mfma_f32_32x32x16_bf16 v[112:127], v[186:189], v[246:249], v[112:127]
	s_waitcnt lgkmcnt(0)
	v_mfma_f32_32x32x16_bf16 v[128:143], v[194:197], v[234:237], v[128:143]
	v_mfma_f32_32x32x16_bf16 v[112:127], v[226:229], v[234:237], v[112:127]

.LBB0_1192:
	ds_read_b128 v[10:13], v154
	ds_read_b128 v[4:7], v154 offset:8192
	ds_read_b128 v[174:177], v155
	ds_read_b128 v[178:181], v155 offset:8192
	ds_read_b128 v[186:189], v156
	ds_read_b128 v[190:193], v156 offset:8192
	ds_read_b128 v[226:229], v157
	ds_read_b128 v[230:233], v157 offset:8192
	v_max3_f32 v0, v128, v112, v129
	v_max3_f32 v1, v113, v130, v114
	s_nop 0
	v_max3_f32 v0, v0, v131, v115
	v_max3_f32 v1, v1, v132, v116
	s_nop 0
	v_max3_f32 v0, v0, v133, v117
	v_max3_f32 v1, v1, v134, v118
	s_nop 0
	v_max3_f32 v0, v0, v135, v119
	v_max3_f32 v1, v1, v136, v120
	s_nop 0
	v_max3_f32 v0, v0, v137, v121
	v_max3_f32 v1, v1, v138, v122
	s_nop 0
	v_max3_f32 v0, v0, v139, v123
	v_max3_f32 v1, v1, v140, v124
	s_nop 0
	v_max3_f32 v0, v0, v141, v125
	v_max3_f32 v1, v1, v142, v126
	s_nop 0
	v_max3_f32 v0, v0, v1, v143
	v_max_f32_e32 v0, v0, v127
	v_mov_b32_e32 v1, v0
	s_nop 1
	v_permlane32_swap_b32_e32 v0, v1
	v_max_f32_e32 v0, v0, v1
	v_cmp_lt_f32_e32 vcc, s37, v0
	s_cbranch_vccz .LBB0_1194
	v_max_f32_e32 v0, v0, v0
	v_max_f32_e32 v1, 0, v0
	v_exp_f32_e64 v0, -v1
	v_add_f32_e32 v165, v165, v1
	v_sub_f32_e32 v143, v143, v1
	v_sub_f32_e32 v142, v142, v1
	v_pk_mul_f32 v[62:63], v[62:63], v[0:1] op_sel_hi:[1,0]
	v_pk_mul_f32 v[60:61], v[60:61], v[0:1] op_sel_hi:[1,0]
	v_pk_mul_f32 v[58:59], v[58:59], v[0:1] op_sel_hi:[1,0]
	v_pk_mul_f32 v[56:57], v[56:57], v[0:1] op_sel_hi:[1,0]
	v_pk_mul_f32 v[54:55], v[54:55], v[0:1] op_sel_hi:[1,0]
	v_pk_mul_f32 v[52:53], v[52:53], v[0:1] op_sel_hi:[1,0]
	v_pk_mul_f32 v[50:51], v[50:51], v[0:1] op_sel_hi:[1,0]
	v_pk_mul_f32 v[48:49], v[48:49], v[0:1] op_sel_hi:[1,0]
	v_pk_mul_f32 v[78:79], v[78:79], v[0:1] op_sel_hi:[1,0]
	v_pk_mul_f32 v[76:77], v[76:77], v[0:1] op_sel_hi:[1,0]
	v_pk_mul_f32 v[74:75], v[74:75], v[0:1] op_sel_hi:[1,0]
	v_pk_mul_f32 v[72:73], v[72:73], v[0:1] op_sel_hi:[1,0]
	v_pk_mul_f32 v[70:71], v[70:71], v[0:1] op_sel_hi:[1,0]
	v_pk_mul_f32 v[68:69], v[68:69], v[0:1] op_sel_hi:[1,0]
	v_pk_mul_f32 v[66:67], v[66:67], v[0:1] op_sel_hi:[1,0]
	v_pk_mul_f32 v[64:65], v[64:65], v[0:1] op_sel_hi:[1,0]
	v_pk_mul_f32 v[46:47], v[46:47], v[0:1] op_sel_hi:[1,0]
	v_pk_mul_f32 v[44:45], v[44:45], v[0:1] op_sel_hi:[1,0]
	v_pk_mul_f32 v[42:43], v[42:43], v[0:1] op_sel_hi:[1,0]
	v_pk_mul_f32 v[40:41], v[40:41], v[0:1] op_sel_hi:[1,0]
	v_pk_mul_f32 v[38:39], v[38:39], v[0:1] op_sel_hi:[1,0]
	v_pk_mul_f32 v[36:37], v[36:37], v[0:1] op_sel_hi:[1,0]
	v_pk_mul_f32 v[34:35], v[34:35], v[0:1] op_sel_hi:[1,0]
	v_pk_mul_f32 v[32:33], v[32:33], v[0:1] op_sel_hi:[1,0]
	v_pk_mul_f32 v[30:31], v[30:31], v[0:1] op_sel_hi:[1,0]
	v_pk_mul_f32 v[28:29], v[28:29], v[0:1] op_sel_hi:[1,0]
	v_pk_mul_f32 v[26:27], v[26:27], v[0:1] op_sel_hi:[1,0]
	v_pk_mul_f32 v[24:25], v[24:25], v[0:1] op_sel_hi:[1,0]
	v_pk_mul_f32 v[22:23], v[22:23], v[0:1] op_sel_hi:[1,0]
	v_pk_mul_f32 v[20:21], v[20:21], v[0:1] op_sel_hi:[1,0]
	v_pk_mul_f32 v[18:19], v[18:19], v[0:1] op_sel_hi:[1,0]
	v_pk_mul_f32 v[16:17], v[16:17], v[0:1] op_sel_hi:[1,0]
	v_sub_f32_e32 v141, v141, v1
	v_sub_f32_e32 v140, v140, v1
	v_sub_f32_e32 v139, v139, v1
	v_sub_f32_e32 v138, v138, v1
	v_sub_f32_e32 v137, v137, v1
	v_sub_f32_e32 v136, v136, v1
	v_sub_f32_e32 v135, v135, v1
	v_sub_f32_e32 v134, v134, v1
	v_sub_f32_e32 v133, v133, v1
	v_sub_f32_e32 v132, v132, v1
	v_sub_f32_e32 v131, v131, v1
	v_sub_f32_e32 v130, v130, v1
	v_sub_f32_e32 v129, v129, v1
	v_sub_f32_e32 v128, v128, v1
	v_sub_f32_e32 v127, v127, v1
	v_sub_f32_e32 v126, v126, v1
	v_sub_f32_e32 v125, v125, v1
	v_sub_f32_e32 v124, v124, v1
	v_sub_f32_e32 v123, v123, v1
	v_sub_f32_e32 v122, v122, v1
	v_sub_f32_e32 v121, v121, v1
	v_sub_f32_e32 v120, v120, v1
	v_sub_f32_e32 v119, v119, v1
	v_sub_f32_e32 v118, v118, v1
	v_sub_f32_e32 v117, v117, v1
	v_sub_f32_e32 v116, v116, v1
	v_sub_f32_e32 v115, v115, v1
	v_sub_f32_e32 v114, v114, v1
	v_sub_f32_e32 v113, v113, v1
	v_sub_f32_e32 v112, v112, v1
	v_mul_f32_e32 v161, v161, v0
.LBB0_1194:
	s_and_b64 vcc, exec, s[42:43]
	s_cbranch_vccnz .LBB0_1196
	s_waitcnt lgkmcnt(6)
	v_mfma_f32_32x32x16_bf16 v[96:111], v[10:13], v[238:241], 0
	v_mfma_f32_32x32x16_bf16 v[80:95], v[4:7], v[238:241], 0
	s_waitcnt lgkmcnt(4)
	v_mfma_f32_32x32x16_bf16 v[96:111], v[174:177], v[242:245], v[96:111]
	v_mfma_f32_32x32x16_bf16 v[80:95], v[178:181], v[242:245], v[80:95]
	s_waitcnt lgkmcnt(2)
	v_mfma_f32_32x32x16_bf16 v[96:111], v[186:189], v[246:249], v[96:111]
	v_mfma_f32_32x32x16_bf16 v[80:95], v[190:193], v[246:249], v[80:95]
	s_waitcnt lgkmcnt(0)
	v_mfma_f32_32x32x16_bf16 v[96:111], v[226:229], v[234:237], v[96:111]
	v_mfma_f32_32x32x16_bf16 v[80:95], v[230:233], v[234:237], v[80:95]
